# lists: counted vmcnt(4) in the compaction loop (list stores always issued, stay in flight) instead of vmcnt(0)
# baseline (speedup 1.0000x reference)
.LBB0_1167:
	v_mul_hi_i32 v0, v144, s14
	v_add_u32_e32 v0, v0, v144
	v_lshrrev_b32_e32 v1, 31, v0
	v_ashrrev_i32_e32 v0, 4, v0
	v_add_u32_e32 v0, v0, v1
	v_mad_u64_u32 v[16:17], s[0:1], v0, s15, v[144:145]
	v_lshlrev_b32_e32 v2, 8, v16
	v_add_u32_e32 v1, 0x100, v2
	v_cmp_gt_i32_e64 s[0:1], s33, v1
	v_mov_b32_e32 v26, 0
	s_and_saveexec_b64 s[42:43], s[0:1]
	s_cbranch_execz .LBB0_1189
	v_ashrrev_i32_e32 v1, 31, v0
	v_lshlrev_b64 v[20:21], 15, v[0:1]
	v_lshl_add_u64 v[4:5], s[8:9], 0, v[20:21]
	v_ashrrev_i32_e32 v3, 31, v2
	v_lshl_add_u64 v[2:3], v[2:3], 2, v[4:5]
	v_lshl_add_u64 v[2:3], v[2:3], 0, v[10:11]
	global_load_dwordx4 v[4:7], v[2:3], off offset:1024
	v_not_b32_e32 v1, v16
	v_lshl_add_u32 v1, v1, 7, v23
	v_mov_b64_e32 v[2:3], s[28:29]
	v_mul_lo_u32 v18, v1, v16
	v_mad_i64_i32 v[2:3], s[0:1], v0, s35, v[2:3]
	v_ashrrev_i32_e32 v19, 31, v18
	v_mul_lo_u32 v1, v0, s46
	v_lshl_add_u64 v[18:19], v[18:19], 1, v[2:3]
	v_sub_u32_e32 v2, v22, v1
	v_ashrrev_i32_e32 v3, 31, v2
	v_lshl_add_u64 v[2:3], v[2:3], 2, v[20:21]
	v_lshl_add_u64 v[20:21], v[14:15], 0, v[2:3]
	v_mul_lo_u32 v17, v0, s47
	s_mov_b32 s52, 0
	s_mov_b64 s[44:45], 0
	s_waitcnt vmcnt(0)
	s_branch .LBB0_1170
.LBB0_1169:
	s_or_b64 exec, exec, s[2:3]
	v_add_u32_e32 v17, 0x100, v17
	s_bcnt1_i32_b64 s0, s[0:1]
	v_add_u32_e32 v4, v13, v17
	s_add_i32 s52, s48, s0
	v_cmp_lt_i32_e64 s[0:1], s50, v4
	v_lshl_add_u64 v[20:21], v[20:21], 0, s[40:41]
	s_or_b64 s[44:45], s[0:1], s[44:45]
	v_mov_b32_e32 v26, s52
	s_waitcnt vmcnt(4)
	v_mov_b64_e32 v[4:5], v[0:1]
	v_mov_b64_e32 v[6:7], v[2:3]
	s_andn2_b64 exec, exec, s[44:45]
	s_cbranch_execz .LBB0_1188
.LBB0_1170:
	v_add3_u32 v26, v13, v17, s10
	v_cmp_gt_i32_e64 s[0:1], s46, v26
	s_nop 0
	v_mov_b64_e32 v[0:1], v[4:5]
	v_mov_b64_e32 v[2:3], v[6:7]
	s_and_saveexec_b64 s[2:3], s[0:1]
	s_cbranch_execz .LBB0_1172
	global_load_dwordx4 v[0:3], v[20:21], off
.LBB0_1172:
	s_or_b64 exec, exec, s[2:3]
	v_cmp_ne_u32_sdwa s[0:1], v4, v16 src0_sel:BYTE_0 src1_sel:DWORD
	v_mov_b32_e32 v27, 0
	s_mov_b64 s[4:5], -1
	s_and_saveexec_b64 s[48:49], s[0:1]
	v_cmp_eq_u32_sdwa s[0:1], v4, v16 src0_sel:BYTE_2 src1_sel:DWORD
	v_cmp_eq_u32_sdwa s[2:3], v4, v16 src0_sel:BYTE_1 src1_sel:DWORD
	s_nop 0
	v_cndmask_b32_e64 v27, v24, v25, s[0:1]
	s_or_b64 s[0:1], s[2:3], s[0:1]
	v_cndmask_b32_e64 v27, v27, v23, s[2:3]
	s_orn2_b64 s[4:5], s[0:1], exec
	s_or_b64 exec, exec, s[48:49]
	v_cndmask_b32_e64 v4, 0, 1, s[4:5]
	v_cmp_ne_u32_e64 s[2:3], 0, v4
	s_and_saveexec_b64 s[0:1], s[4:5]
	s_nop 0
	v_and_b32_e32 v28, s2, v12
	v_and_b32_e32 v4, s3, v9
	v_bcnt_u32_b32 v28, v28, 0
	v_bcnt_u32_b32 v4, v4, v28
	v_add_u32_e32 v28, s52, v4
	v_ashrrev_i32_e32 v29, 31, v28
	v_or3_b32 v4, v8, v27, v26
	v_lshl_add_u64 v[28:29], v[28:29], 1, v[18:19]
	global_store_short v[28:29], v4, off
.LBB0_1176:
	s_or_b64 exec, exec, s[0:1]
	v_cmp_ne_u32_sdwa s[4:5], v5, v16 src0_sel:BYTE_0 src1_sel:DWORD
	v_mov_b32_e32 v4, 0
	s_mov_b64 s[0:1], -1
	s_and_saveexec_b64 s[48:49], s[4:5]
	v_cmp_eq_u32_sdwa s[0:1], v5, v16 src0_sel:BYTE_2 src1_sel:DWORD
	v_cmp_eq_u32_sdwa s[4:5], v5, v16 src0_sel:BYTE_1 src1_sel:DWORD
	s_nop 0
	v_cndmask_b32_e64 v4, v24, v25, s[0:1]
	s_or_b64 s[0:1], s[4:5], s[0:1]
	v_cndmask_b32_e64 v4, v4, v23, s[4:5]
	s_orn2_b64 s[0:1], s[0:1], exec
	s_or_b64 exec, exec, s[48:49]
	s_bcnt1_i32_b64 s2, s[2:3]
	v_cndmask_b32_e64 v5, 0, 1, s[0:1]
	s_add_i32 s52, s52, s2
	v_cmp_ne_u32_e64 s[2:3], 0, v5
	s_and_saveexec_b64 s[4:5], s[0:1]
	s_nop 0
	v_and_b32_e32 v27, s2, v12
	v_and_b32_e32 v5, s3, v9
	v_bcnt_u32_b32 v27, v27, 0
	v_bcnt_u32_b32 v5, v5, v27
	v_add_u32_e32 v28, s52, v5
	v_or3_b32 v4, v8, v4, v26
	v_ashrrev_i32_e32 v29, 31, v28
	v_or_b32_e32 v27, 1, v4
	v_lshl_add_u64 v[4:5], v[28:29], 1, v[18:19]
	global_store_short v[4:5], v27, off
.LBB0_1180:
	s_or_b64 exec, exec, s[4:5]
	v_cmp_ne_u32_sdwa s[4:5], v6, v16 src0_sel:BYTE_0 src1_sel:DWORD
	v_mov_b32_e32 v4, 0
	s_mov_b64 s[0:1], -1
	s_and_saveexec_b64 s[48:49], s[4:5]
	v_cmp_eq_u32_sdwa s[0:1], v6, v16 src0_sel:BYTE_2 src1_sel:DWORD
	v_cmp_eq_u32_sdwa s[4:5], v6, v16 src0_sel:BYTE_1 src1_sel:DWORD
	s_nop 0
	v_cndmask_b32_e64 v4, v24, v25, s[0:1]
	s_or_b64 s[0:1], s[4:5], s[0:1]
	v_cndmask_b32_e64 v4, v4, v23, s[4:5]
	s_orn2_b64 s[0:1], s[0:1], exec
	s_or_b64 exec, exec, s[48:49]
	s_bcnt1_i32_b64 s2, s[2:3]
	v_cndmask_b32_e64 v5, 0, 1, s[0:1]
	s_add_i32 s52, s52, s2
	v_cmp_ne_u32_e64 s[2:3], 0, v5
	s_and_saveexec_b64 s[4:5], s[0:1]
	s_nop 0
	v_and_b32_e32 v6, s2, v12
	v_and_b32_e32 v5, s3, v9
	v_bcnt_u32_b32 v6, v6, 0
	v_bcnt_u32_b32 v5, v5, v6
	v_add_u32_e32 v28, s52, v5
	v_or3_b32 v4, v8, v4, v26
	v_ashrrev_i32_e32 v29, 31, v28
	v_or_b32_e32 v6, 2, v4
	v_lshl_add_u64 v[4:5], v[28:29], 1, v[18:19]
	global_store_short v[4:5], v6, off
.LBB0_1184:
	s_or_b64 exec, exec, s[4:5]
	v_cmp_ne_u32_sdwa s[0:1], v7, v16 src0_sel:BYTE_0 src1_sel:DWORD
	v_mov_b32_e32 v4, 0
	s_mov_b64 s[4:5], -1
	s_and_saveexec_b64 s[48:49], s[0:1]
	v_cmp_eq_u32_sdwa s[0:1], v7, v16 src0_sel:BYTE_2 src1_sel:DWORD
	v_cmp_eq_u32_sdwa s[4:5], v7, v16 src0_sel:BYTE_1 src1_sel:DWORD
	s_nop 0
	v_cndmask_b32_e64 v4, v24, v25, s[0:1]
	s_or_b64 s[0:1], s[4:5], s[0:1]
	v_cndmask_b32_e64 v4, v4, v23, s[4:5]
	s_orn2_b64 s[4:5], s[0:1], exec
	s_or_b64 exec, exec, s[48:49]
	s_bcnt1_i32_b64 s0, s[2:3]
	v_cndmask_b32_e64 v5, 0, 1, s[4:5]
	s_add_i32 s48, s52, s0
	v_cmp_ne_u32_e64 s[0:1], 0, v5
	s_and_saveexec_b64 s[2:3], s[4:5]
	s_nop 0
	v_and_b32_e32 v6, s0, v12
	v_and_b32_e32 v5, s1, v9
	v_bcnt_u32_b32 v6, v6, 0
	v_bcnt_u32_b32 v5, v5, v6
	v_add_u32_e32 v6, s48, v5
	v_or3_b32 v4, v8, v4, v26
	v_ashrrev_i32_e32 v7, 31, v6
	v_or_b32_e32 v26, 3, v4
	v_lshl_add_u64 v[4:5], v[6:7], 1, v[18:19]
	global_store_short v[4:5], v26, off
	s_branch .LBB0_1169
